# GEMM phases: static s_setprio 1 for waves 0-3 instead of waves 4-7 (per-half comparison)
# baseline (speedup 1.0000x reference)
.LBB0_296:
	s_or_b64 exec, exec, s[6:7]
	s_cmpk_lt_i32 s2, 0x37b
	s_cselect_b64 s[0:1], -1, 0
	v_mov_b32_e32 v128, v254
	v_mov_b32_e32 v8, v254
	s_waitcnt lgkmcnt(0)
	s_barrier
	v_cmp_gt_u32_e32 vcc, 0x100, v254
	s_cbranch_vccz .Lprio_skip1
	s_setprio 1

.LBB0_527:
	s_or_b64 exec, exec, s[6:7]
	s_waitcnt lgkmcnt(0)
	v_mov_b32_e32 v0, v254
	s_barrier
	v_cmp_gt_u32_e32 vcc, 0x100, v254
	s_cbranch_vccz .Lprio_skip2
	s_setprio 1

.LBB0_839:
	s_or_b64 exec, exec, s[6:7]
	s_waitcnt lgkmcnt(0)
	v_mov_b32_e32 v0, v254
	v_readlane_b32 s0, v255, 10
	s_barrier
	v_cmp_gt_u32_e32 vcc, 0x100, v254
	s_cbranch_vccz .Lprio_skip5
	s_setprio 1

.LBB0_979:
	s_or_b64 exec, exec, s[6:7]
	s_add_u32 s48, s26, 0x13200000
	s_addc_u32 s49, s27, 0
	s_cmpk_lt_i32 s2, 0x580
	s_cselect_b64 s[56:57], -1, 0
	v_mov_b32_e32 v128, v254
	v_mov_b32_e32 v9, v254
	s_waitcnt lgkmcnt(0)
	s_barrier
	v_cmp_gt_u32_e32 vcc, 0x100, v254
	s_cbranch_vccz .Lprio_skip7
	s_setprio 1

.LBB0_1083:
	s_or_b64 exec, exec, s[6:7]
	v_readlane_b32 s0, v255, 7
	s_waitcnt lgkmcnt(0)
	v_mov_b32_e32 v0, v254
	v_mov_b32_e32 v8, v254
	v_readlane_b32 s1, v255, 8
	s_barrier
	v_cmp_gt_u32_e32 vcc, 0x100, v254
	s_cbranch_vccz .Lprio_skip8
	s_setprio 1

.LBB0_1669:
	s_or_b64 exec, exec, s[6:7]
	s_waitcnt lgkmcnt(0)
	v_mov_b32_e32 v0, v254
	v_mov_b32_e32 v9, v254
	s_barrier
	v_cmp_gt_u32_e32 vcc, 0x100, v254
	s_cbranch_vccz .Lprio_skip16
	s_setprio 1
